# GEMM K loops: loop counter / address increment SALU moved ahead of the loop-back barrier (partial back-edge rotation), on top of the spread in-loop copy block
# baseline (speedup 1.0000x reference)
.LBB0_133:
	ds_read_b128 v[146:149], v155
	ds_read_b128 v[158:161], v155 offset:1024
	ds_read_b128 v[162:165], v155 offset:2048
	ds_read_b128 v[166:169], v155 offset:3072
	ds_read_b128 v[170:173], v156
	ds_read_b128 v[174:177], v156 offset:1024
	ds_read_b128 v[178:181], v156 offset:2048
	ds_read_b128 v[182:185], v156 offset:3072
	s_add_u32 s40, s34, 0xfffc0080
	s_addc_u32 s41, s35, -1
	s_cmp_eq_u32 s72, 12
	s_cselect_b32 s43, s3, s41
	s_cselect_b32 s42, s7, s40
	s_cselect_b32 s41, s17, s65
	s_cselect_b32 s40, s19, s64
	v_lshl_add_u64 v[150:151], s[34:35], 0, v[138:139]
	s_add_i32 m0, s50, 0xc000
	ds_read_b128 v[186:189], v157
	ds_read_b128 v[190:193], v157 offset:1024
	ds_read_b128 v[194:197], v157 offset:2048
	ds_read_b128 v[198:201], v157 offset:3072
	ds_read_b128 v[202:205], v157 offset:4096
	ds_read_b128 v[206:209], v157 offset:5120
	ds_read_b128 v[210:213], v157 offset:6144
	ds_read_b128 v[214:217], v157 offset:7168
	global_load_lds_dwordx4 v[150:151], off
	v_lshl_add_u64 v[150:151], s[34:35], 0, v[140:141]
	s_add_i32 m0, s50, 0xe000
	s_nop 0
	global_load_lds_dwordx4 v[150:151], off
	s_waitcnt vmcnt(8)
	s_waitcnt lgkmcnt(0)
	s_barrier
	s_setprio 1
	s_waitcnt lgkmcnt(0)
	v_mfma_f32_16x16x32_bf16 v[124:127], v[146:149], v[186:189], v[124:127]
	v_mfma_f32_16x16x32_bf16 v[120:123], v[162:165], v[186:189], v[120:123]
	v_mfma_f32_16x16x32_bf16 v[108:111], v[146:149], v[194:197], v[108:111]
	v_mfma_f32_16x16x32_bf16 v[104:107], v[162:165], v[194:197], v[104:107]
	v_mfma_f32_16x16x32_bf16 v[92:95], v[146:149], v[202:205], v[92:95]
	v_mfma_f32_16x16x32_bf16 v[88:91], v[162:165], v[202:205], v[88:91]
	v_mfma_f32_16x16x32_bf16 v[76:79], v[146:149], v[210:213], v[76:79]
	v_mfma_f32_16x16x32_bf16 v[72:75], v[162:165], v[210:213], v[72:75]
	v_mfma_f32_16x16x32_bf16 v[124:127], v[158:161], v[190:193], v[124:127]
	v_mfma_f32_16x16x32_bf16 v[120:123], v[166:169], v[190:193], v[120:123]
	v_mfma_f32_16x16x32_bf16 v[108:111], v[158:161], v[198:201], v[108:111]
	v_mfma_f32_16x16x32_bf16 v[104:107], v[166:169], v[198:201], v[104:107]
	v_mfma_f32_16x16x32_bf16 v[92:95], v[158:161], v[206:209], v[92:95]
	v_mfma_f32_16x16x32_bf16 v[88:91], v[166:169], v[206:209], v[88:91]
	v_mfma_f32_16x16x32_bf16 v[76:79], v[158:161], v[214:217], v[76:79]
	v_mfma_f32_16x16x32_bf16 v[72:75], v[166:169], v[214:217], v[72:75]
	s_setprio 0
	s_setprio 1
	v_mfma_f32_16x16x32_bf16 v[116:119], v[170:173], v[186:189], v[116:119]
	v_mfma_f32_16x16x32_bf16 v[112:115], v[178:181], v[186:189], v[112:115]
	v_mfma_f32_16x16x32_bf16 v[100:103], v[170:173], v[194:197], v[100:103]
	v_mfma_f32_16x16x32_bf16 v[96:99], v[178:181], v[194:197], v[96:99]
	v_mfma_f32_16x16x32_bf16 v[84:87], v[170:173], v[202:205], v[84:87]
	v_mfma_f32_16x16x32_bf16 v[80:83], v[178:181], v[202:205], v[80:83]
	v_mfma_f32_16x16x32_bf16 v[68:71], v[170:173], v[210:213], v[68:71]
	v_mfma_f32_16x16x32_bf16 v[64:67], v[178:181], v[210:213], v[64:67]
	v_mfma_f32_16x16x32_bf16 v[116:119], v[174:177], v[190:193], v[116:119]
	v_mfma_f32_16x16x32_bf16 v[112:115], v[182:185], v[190:193], v[112:115]
	v_mfma_f32_16x16x32_bf16 v[100:103], v[174:177], v[198:201], v[100:103]
	v_mfma_f32_16x16x32_bf16 v[96:99], v[182:185], v[198:201], v[96:99]
	v_mfma_f32_16x16x32_bf16 v[84:87], v[174:177], v[206:209], v[84:87]
	v_mfma_f32_16x16x32_bf16 v[80:83], v[182:185], v[206:209], v[80:83]
	v_mfma_f32_16x16x32_bf16 v[68:71], v[174:177], v[214:217], v[68:71]
	v_mfma_f32_16x16x32_bf16 v[64:67], v[182:185], v[214:217], v[64:67]
	s_setprio 0
	s_barrier
	s_add_i32 s73, s59, s45
	v_lshl_add_u64 v[150:151], s[40:41], 0, v[130:131]
	s_mov_b32 m0, s73
	ds_read_b128 v[186:189], v157 offset:16384
	ds_read_b128 v[190:193], v157 offset:17408
	ds_read_b128 v[194:197], v157 offset:18432
	ds_read_b128 v[198:201], v157 offset:19456
	ds_read_b128 v[202:205], v157 offset:20480
	ds_read_b128 v[206:209], v157 offset:21504
	ds_read_b128 v[210:213], v157 offset:22528
	ds_read_b128 v[214:217], v157 offset:23552
	global_load_lds_dwordx4 v[150:151], off
	s_add_i32 m0, s73, 0x2000
	s_add_u32 s74, s40, 0x40000
	v_lshl_add_u64 v[218:219], s[40:41], 0, v[134:135]
	s_addc_u32 s75, s41, 0
	s_add_i32 s73, s60, s45
	global_load_lds_dwordx4 v[218:219], off
	v_lshl_add_u64 v[220:221], s[74:75], 0, v[130:131]
	s_mov_b32 m0, s73
	v_lshl_add_u64 v[224:225], s[42:43], 0, v[132:133]
	global_load_lds_dwordx4 v[220:221], off
	v_lshl_add_u64 v[220:221], s[74:75], 0, v[134:135]
	s_add_i32 m0, s73, 0x2000
	s_nop 0
	global_load_lds_dwordx4 v[220:221], off
	v_lshl_add_u64 v[220:221], s[42:43], 0, v[128:129]
	s_mov_b32 m0, s50
	s_nop 0
	global_load_lds_dwordx4 v[220:221], off
	s_mov_b32 m0, s51
	s_nop 0
	global_load_lds_dwordx4 v[224:225], off
	s_waitcnt vmcnt(8)
	s_waitcnt lgkmcnt(0)
	s_barrier
	s_setprio 1
	s_waitcnt lgkmcnt(0)
	v_mfma_f32_16x16x32_bf16 v[60:63], v[146:149], v[186:189], v[60:63]
	v_mfma_f32_16x16x32_bf16 v[56:59], v[162:165], v[186:189], v[56:59]
	v_mfma_f32_16x16x32_bf16 v[44:47], v[146:149], v[194:197], v[44:47]
	v_mfma_f32_16x16x32_bf16 v[40:43], v[162:165], v[194:197], v[40:43]
	v_mfma_f32_16x16x32_bf16 v[28:31], v[146:149], v[202:205], v[28:31]
	v_mfma_f32_16x16x32_bf16 v[24:27], v[162:165], v[202:205], v[24:27]
	v_mfma_f32_16x16x32_bf16 v[12:15], v[146:149], v[210:213], v[12:15]
	v_mfma_f32_16x16x32_bf16 v[8:11], v[162:165], v[210:213], v[8:11]
	v_mfma_f32_16x16x32_bf16 v[60:63], v[158:161], v[190:193], v[60:63]
	v_mfma_f32_16x16x32_bf16 v[56:59], v[166:169], v[190:193], v[56:59]
	v_mfma_f32_16x16x32_bf16 v[44:47], v[158:161], v[198:201], v[44:47]
	v_mfma_f32_16x16x32_bf16 v[40:43], v[166:169], v[198:201], v[40:43]
	v_mfma_f32_16x16x32_bf16 v[28:31], v[158:161], v[206:209], v[28:31]
	v_mfma_f32_16x16x32_bf16 v[24:27], v[166:169], v[206:209], v[24:27]
	v_mfma_f32_16x16x32_bf16 v[12:15], v[158:161], v[214:217], v[12:15]
	v_mfma_f32_16x16x32_bf16 v[8:11], v[166:169], v[214:217], v[8:11]
	s_setprio 0
	s_setprio 1
	v_mfma_f32_16x16x32_bf16 v[52:55], v[170:173], v[186:189], v[52:55]
	v_mfma_f32_16x16x32_bf16 v[48:51], v[178:181], v[186:189], v[48:51]
	v_mfma_f32_16x16x32_bf16 v[36:39], v[170:173], v[194:197], v[36:39]
	v_mfma_f32_16x16x32_bf16 v[32:35], v[178:181], v[194:197], v[32:35]
	v_mfma_f32_16x16x32_bf16 v[20:23], v[170:173], v[202:205], v[20:23]
	v_mfma_f32_16x16x32_bf16 v[16:19], v[178:181], v[202:205], v[16:19]
	v_mfma_f32_16x16x32_bf16 v[4:7], v[170:173], v[210:213], v[4:7]
	v_mfma_f32_16x16x32_bf16 v[0:3], v[178:181], v[210:213], v[0:3]
	v_mfma_f32_16x16x32_bf16 v[52:55], v[174:177], v[190:193], v[52:55]
	v_mfma_f32_16x16x32_bf16 v[48:51], v[182:185], v[190:193], v[48:51]
	v_mfma_f32_16x16x32_bf16 v[36:39], v[174:177], v[198:201], v[36:39]
	v_mfma_f32_16x16x32_bf16 v[32:35], v[182:185], v[198:201], v[32:35]
	v_mfma_f32_16x16x32_bf16 v[20:23], v[174:177], v[206:209], v[20:23]
	v_mfma_f32_16x16x32_bf16 v[16:19], v[182:185], v[206:209], v[16:19]
	v_mfma_f32_16x16x32_bf16 v[4:7], v[174:177], v[214:217], v[4:7]
	v_mfma_f32_16x16x32_bf16 v[0:3], v[182:185], v[214:217], v[0:3]
	s_setprio 0
	s_barrier
	s_add_i32 s73, 0, 0x18000
	v_add_u32_e32 v136, s73, v154
	s_add_i32 s74, 0, 0x1c000
	ds_read_b128 v[146:149], v136
	ds_read_b128 v[158:161], v136 offset:1024
	ds_read_b128 v[162:165], v136 offset:2048
	ds_read_b128 v[166:169], v136 offset:3072
	v_add_u32_e32 v136, s74, v154
	ds_read_b128 v[170:173], v136
	ds_read_b128 v[174:177], v136 offset:1024
	ds_read_b128 v[178:181], v136 offset:2048
	ds_read_b128 v[182:185], v136 offset:3072
	s_add_u32 s42, s42, 0x40000
	s_addc_u32 s43, s43, 0
	s_mov_b32 m0, s52
	v_lshl_add_u64 v[226:227], s[42:43], 0, v[128:129]
	ds_read_b128 v[186:189], v157 offset:32768
	ds_read_b128 v[190:193], v157 offset:33792
	ds_read_b128 v[194:197], v157 offset:34816
	ds_read_b128 v[198:201], v157 offset:35840
	ds_read_b128 v[202:205], v157 offset:36864
	ds_read_b128 v[206:209], v157 offset:37888
	ds_read_b128 v[210:213], v157 offset:38912
	ds_read_b128 v[214:217], v157 offset:39936
	global_load_lds_dwordx4 v[226:227], off
	v_lshl_add_u64 v[226:227], s[42:43], 0, v[132:133]
	s_mov_b32 m0, s53
	s_nop 0
	global_load_lds_dwordx4 v[226:227], off
	s_waitcnt vmcnt(8)
	s_waitcnt lgkmcnt(0)
	s_barrier
	s_setprio 1
	s_waitcnt lgkmcnt(0)
	v_mfma_f32_16x16x32_bf16 v[124:127], v[146:149], v[186:189], v[124:127]
	v_mfma_f32_16x16x32_bf16 v[120:123], v[162:165], v[186:189], v[120:123]
	v_mfma_f32_16x16x32_bf16 v[108:111], v[146:149], v[194:197], v[108:111]
	v_mfma_f32_16x16x32_bf16 v[104:107], v[162:165], v[194:197], v[104:107]
	v_mfma_f32_16x16x32_bf16 v[92:95], v[146:149], v[202:205], v[92:95]
	v_mfma_f32_16x16x32_bf16 v[88:91], v[162:165], v[202:205], v[88:91]
	v_mfma_f32_16x16x32_bf16 v[76:79], v[146:149], v[210:213], v[76:79]
	v_mfma_f32_16x16x32_bf16 v[72:75], v[162:165], v[210:213], v[72:75]
	v_mfma_f32_16x16x32_bf16 v[124:127], v[158:161], v[190:193], v[124:127]
	v_mfma_f32_16x16x32_bf16 v[120:123], v[166:169], v[190:193], v[120:123]
	v_mfma_f32_16x16x32_bf16 v[108:111], v[158:161], v[198:201], v[108:111]
	v_mfma_f32_16x16x32_bf16 v[104:107], v[166:169], v[198:201], v[104:107]
	v_mfma_f32_16x16x32_bf16 v[92:95], v[158:161], v[206:209], v[92:95]
	v_mfma_f32_16x16x32_bf16 v[88:91], v[166:169], v[206:209], v[88:91]
	v_mfma_f32_16x16x32_bf16 v[76:79], v[158:161], v[214:217], v[76:79]
	v_mfma_f32_16x16x32_bf16 v[72:75], v[166:169], v[214:217], v[72:75]
	s_setprio 0
	s_setprio 1
	v_mfma_f32_16x16x32_bf16 v[116:119], v[170:173], v[186:189], v[116:119]
	v_mfma_f32_16x16x32_bf16 v[112:115], v[178:181], v[186:189], v[112:115]
	v_mfma_f32_16x16x32_bf16 v[100:103], v[170:173], v[194:197], v[100:103]
	v_mfma_f32_16x16x32_bf16 v[96:99], v[178:181], v[194:197], v[96:99]
	v_mfma_f32_16x16x32_bf16 v[84:87], v[170:173], v[202:205], v[84:87]
	v_mfma_f32_16x16x32_bf16 v[80:83], v[178:181], v[202:205], v[80:83]
	v_mfma_f32_16x16x32_bf16 v[68:71], v[170:173], v[210:213], v[68:71]
	v_mfma_f32_16x16x32_bf16 v[64:67], v[178:181], v[210:213], v[64:67]
	v_mfma_f32_16x16x32_bf16 v[116:119], v[174:177], v[190:193], v[116:119]
	v_mfma_f32_16x16x32_bf16 v[112:115], v[182:185], v[190:193], v[112:115]
	v_mfma_f32_16x16x32_bf16 v[100:103], v[174:177], v[198:201], v[100:103]
	v_mfma_f32_16x16x32_bf16 v[96:99], v[182:185], v[198:201], v[96:99]
	v_mfma_f32_16x16x32_bf16 v[84:87], v[174:177], v[206:209], v[84:87]
	v_mfma_f32_16x16x32_bf16 v[80:83], v[182:185], v[206:209], v[80:83]
	v_mfma_f32_16x16x32_bf16 v[68:71], v[174:177], v[214:217], v[68:71]
	v_mfma_f32_16x16x32_bf16 v[64:67], v[182:185], v[214:217], v[64:67]
	s_setprio 0
	s_barrier
	s_add_i32 s42, s73, s45
	v_lshl_add_u64 v[150:151], v[150:151], 0, s[10:11]
	s_mov_b32 m0, s42
	ds_read_b128 v[186:189], v157 offset:49152
	ds_read_b128 v[190:193], v157 offset:50176
	ds_read_b128 v[194:197], v157 offset:51200
	ds_read_b128 v[198:201], v157 offset:52224
	ds_read_b128 v[202:205], v157 offset:53248
	ds_read_b128 v[206:209], v157 offset:54272
	ds_read_b128 v[210:213], v157 offset:55296
	ds_read_b128 v[214:217], v157 offset:56320
	global_load_lds_dwordx4 v[150:151], off
	s_add_i32 m0, s42, 0x2000
	s_add_u32 s40, s40, 0x40080
	v_lshl_add_u64 v[150:151], v[218:219], 0, s[10:11]
	s_addc_u32 s41, s41, 0
	s_add_i32 s42, s74, s45
	global_load_lds_dwordx4 v[150:151], off
	v_lshl_add_u64 v[150:151], s[40:41], 0, v[130:131]
	s_mov_b32 m0, s42
	s_nop 0
	global_load_lds_dwordx4 v[150:151], off
	v_lshl_add_u64 v[150:151], s[40:41], 0, v[134:135]
	s_add_i32 m0, s42, 0x2000
	s_nop 0
	global_load_lds_dwordx4 v[150:151], off
	v_lshl_add_u64 v[150:151], v[220:221], 0, s[10:11]
	s_mov_b32 m0, s57
	s_nop 0
	global_load_lds_dwordx4 v[150:151], off
	v_lshl_add_u64 v[150:151], v[224:225], 0, s[10:11]
	s_mov_b32 m0, s58
	s_nop 0
	global_load_lds_dwordx4 v[150:151], off
	s_waitcnt vmcnt(8)
	s_waitcnt lgkmcnt(0)
	s_barrier
	s_setprio 1
	s_waitcnt lgkmcnt(0)
	v_mfma_f32_16x16x32_bf16 v[60:63], v[146:149], v[186:189], v[60:63]
	v_mfma_f32_16x16x32_bf16 v[56:59], v[162:165], v[186:189], v[56:59]
	v_mfma_f32_16x16x32_bf16 v[44:47], v[146:149], v[194:197], v[44:47]
	v_mfma_f32_16x16x32_bf16 v[40:43], v[162:165], v[194:197], v[40:43]
	v_mfma_f32_16x16x32_bf16 v[28:31], v[146:149], v[202:205], v[28:31]
	v_mfma_f32_16x16x32_bf16 v[24:27], v[162:165], v[202:205], v[24:27]
	v_mfma_f32_16x16x32_bf16 v[12:15], v[146:149], v[210:213], v[12:15]
	v_mfma_f32_16x16x32_bf16 v[8:11], v[162:165], v[210:213], v[8:11]
	v_mfma_f32_16x16x32_bf16 v[60:63], v[158:161], v[190:193], v[60:63]
	v_mfma_f32_16x16x32_bf16 v[56:59], v[166:169], v[190:193], v[56:59]
	v_mfma_f32_16x16x32_bf16 v[44:47], v[158:161], v[198:201], v[44:47]
	v_mfma_f32_16x16x32_bf16 v[40:43], v[166:169], v[198:201], v[40:43]
	v_mfma_f32_16x16x32_bf16 v[28:31], v[158:161], v[206:209], v[28:31]
	v_mfma_f32_16x16x32_bf16 v[24:27], v[166:169], v[206:209], v[24:27]
	v_mfma_f32_16x16x32_bf16 v[12:15], v[158:161], v[214:217], v[12:15]
	v_mfma_f32_16x16x32_bf16 v[8:11], v[166:169], v[214:217], v[8:11]
	s_setprio 0
	s_setprio 1
	v_mfma_f32_16x16x32_bf16 v[52:55], v[170:173], v[186:189], v[52:55]
	v_mfma_f32_16x16x32_bf16 v[48:51], v[178:181], v[186:189], v[48:51]
	v_mfma_f32_16x16x32_bf16 v[36:39], v[170:173], v[194:197], v[36:39]
	v_mfma_f32_16x16x32_bf16 v[32:35], v[178:181], v[194:197], v[32:35]
	v_mfma_f32_16x16x32_bf16 v[20:23], v[170:173], v[202:205], v[20:23]
	v_mfma_f32_16x16x32_bf16 v[16:19], v[178:181], v[202:205], v[16:19]
	v_mfma_f32_16x16x32_bf16 v[4:7], v[170:173], v[210:213], v[4:7]
	v_mfma_f32_16x16x32_bf16 v[0:3], v[178:181], v[210:213], v[0:3]
	v_mfma_f32_16x16x32_bf16 v[52:55], v[174:177], v[190:193], v[52:55]
	v_mfma_f32_16x16x32_bf16 v[48:51], v[182:185], v[190:193], v[48:51]
	v_mfma_f32_16x16x32_bf16 v[36:39], v[174:177], v[198:201], v[36:39]
	v_mfma_f32_16x16x32_bf16 v[32:35], v[182:185], v[198:201], v[32:35]
	v_mfma_f32_16x16x32_bf16 v[20:23], v[174:177], v[206:209], v[20:23]
	v_mfma_f32_16x16x32_bf16 v[16:19], v[182:185], v[206:209], v[16:19]
	v_mfma_f32_16x16x32_bf16 v[4:7], v[174:177], v[214:217], v[4:7]
	v_mfma_f32_16x16x32_bf16 v[0:3], v[182:185], v[214:217], v[0:3]
	s_setprio 0
	s_add_i32 s72, s72, 2
	s_add_u32 s34, s34, 0x100
	s_addc_u32 s35, s35, 0
	s_add_u32 s64, s64, 0x100
	s_addc_u32 s65, s65, 0
	s_cmp_gt_u32 s72, 13
	s_barrier
	s_cbranch_scc0 .LBB0_133
	s_and_b64 vcc, exec, s[12:13]
	s_cbranch_vccz .LBB0_136
	s_barrier

.LBB0_606:
	ds_read_b128 v[128:131], v227
	ds_read_b128 v[132:135], v227 offset:1024
	ds_read_b128 v[136:139], v227 offset:2048
	ds_read_b128 v[140:143], v227 offset:3072
	ds_read_b128 v[144:147], v228
	ds_read_b128 v[148:151], v228 offset:1024
	ds_read_b128 v[152:155], v228 offset:2048
	ds_read_b128 v[156:159], v228 offset:3072
	s_add_u32 s10, s8, 0xfffc0080
	s_addc_u32 s11, s9, -1
	s_cmp_eq_u32 s61, 12
	s_cselect_b32 s13, s1, s11
	s_cselect_b32 s12, s37, s10
	s_cselect_b32 s11, s31, s60
	s_cselect_b32 s10, s58, s59
	v_lshl_add_u64 v[208:209], s[8:9], 0, v[200:201]
	s_add_i32 m0, s3, 0xc000
	ds_read_b128 v[160:163], v229
	ds_read_b128 v[164:167], v229 offset:1024
	ds_read_b128 v[168:171], v229 offset:2048
	ds_read_b128 v[172:175], v229 offset:3072
	ds_read_b128 v[176:179], v229 offset:4096
	ds_read_b128 v[180:183], v229 offset:5120
	ds_read_b128 v[184:187], v229 offset:6144
	ds_read_b128 v[188:191], v229 offset:7168
	global_load_lds_dwordx4 v[208:209], off
	v_lshl_add_u64 v[208:209], s[8:9], 0, v[202:203]
	s_add_i32 m0, s3, 0xe000
	s_nop 0
	global_load_lds_dwordx4 v[208:209], off
	s_waitcnt vmcnt(8)
	s_waitcnt lgkmcnt(0)
	s_barrier
	s_setprio 1
	s_waitcnt lgkmcnt(0)
	v_mfma_f32_16x16x32_bf16 v[124:127], v[128:131], v[160:163], v[124:127]
	v_mfma_f32_16x16x32_bf16 v[120:123], v[136:139], v[160:163], v[120:123]
	v_mfma_f32_16x16x32_bf16 v[108:111], v[128:131], v[168:171], v[108:111]
	v_mfma_f32_16x16x32_bf16 v[104:107], v[136:139], v[168:171], v[104:107]
	v_mfma_f32_16x16x32_bf16 v[92:95], v[128:131], v[176:179], v[92:95]
	v_mfma_f32_16x16x32_bf16 v[88:91], v[136:139], v[176:179], v[88:91]
	v_mfma_f32_16x16x32_bf16 v[76:79], v[128:131], v[184:187], v[76:79]
	v_mfma_f32_16x16x32_bf16 v[72:75], v[136:139], v[184:187], v[72:75]
	v_mfma_f32_16x16x32_bf16 v[124:127], v[132:135], v[164:167], v[124:127]
	v_mfma_f32_16x16x32_bf16 v[120:123], v[140:143], v[164:167], v[120:123]
	v_mfma_f32_16x16x32_bf16 v[108:111], v[132:135], v[172:175], v[108:111]
	v_mfma_f32_16x16x32_bf16 v[104:107], v[140:143], v[172:175], v[104:107]
	v_mfma_f32_16x16x32_bf16 v[92:95], v[132:135], v[180:183], v[92:95]
	v_mfma_f32_16x16x32_bf16 v[88:91], v[140:143], v[180:183], v[88:91]
	v_mfma_f32_16x16x32_bf16 v[76:79], v[132:135], v[188:191], v[76:79]
	v_mfma_f32_16x16x32_bf16 v[72:75], v[140:143], v[188:191], v[72:75]
	s_setprio 0
	s_setprio 1
	v_mfma_f32_16x16x32_bf16 v[116:119], v[144:147], v[160:163], v[116:119]
	v_mfma_f32_16x16x32_bf16 v[112:115], v[152:155], v[160:163], v[112:115]
	v_mfma_f32_16x16x32_bf16 v[100:103], v[144:147], v[168:171], v[100:103]
	v_mfma_f32_16x16x32_bf16 v[96:99], v[152:155], v[168:171], v[96:99]
	v_mfma_f32_16x16x32_bf16 v[84:87], v[144:147], v[176:179], v[84:87]
	v_mfma_f32_16x16x32_bf16 v[80:83], v[152:155], v[176:179], v[80:83]
	v_mfma_f32_16x16x32_bf16 v[68:71], v[144:147], v[184:187], v[68:71]
	v_mfma_f32_16x16x32_bf16 v[64:67], v[152:155], v[184:187], v[64:67]
	v_mfma_f32_16x16x32_bf16 v[116:119], v[148:151], v[164:167], v[116:119]
	v_mfma_f32_16x16x32_bf16 v[112:115], v[156:159], v[164:167], v[112:115]
	v_mfma_f32_16x16x32_bf16 v[100:103], v[148:151], v[172:175], v[100:103]
	v_mfma_f32_16x16x32_bf16 v[96:99], v[156:159], v[172:175], v[96:99]
	v_mfma_f32_16x16x32_bf16 v[84:87], v[148:151], v[180:183], v[84:87]
	v_mfma_f32_16x16x32_bf16 v[80:83], v[156:159], v[180:183], v[80:83]
	v_mfma_f32_16x16x32_bf16 v[68:71], v[148:151], v[188:191], v[68:71]
	v_mfma_f32_16x16x32_bf16 v[64:67], v[156:159], v[188:191], v[64:67]
	s_setprio 0
	s_barrier
	s_add_i32 s62, s55, s33
	v_lshl_add_u64 v[208:209], s[10:11], 0, v[194:195]
	s_mov_b32 m0, s62
	ds_read_b128 v[160:163], v229 offset:16384
	ds_read_b128 v[164:167], v229 offset:17408
	ds_read_b128 v[168:171], v229 offset:18432
	ds_read_b128 v[172:175], v229 offset:19456
	ds_read_b128 v[176:179], v229 offset:20480
	ds_read_b128 v[180:183], v229 offset:21504
	ds_read_b128 v[184:187], v229 offset:22528
	ds_read_b128 v[188:191], v229 offset:23552
	global_load_lds_dwordx4 v[208:209], off
	s_add_i32 m0, s62, 0x2000
	s_add_u32 s62, s10, 0x40000
	v_lshl_add_u64 v[210:211], s[10:11], 0, v[198:199]
	s_addc_u32 s63, s11, 0
	s_add_i32 s64, s56, s33
	global_load_lds_dwordx4 v[210:211], off
	v_lshl_add_u64 v[212:213], s[62:63], 0, v[194:195]
	s_mov_b32 m0, s64
	v_lshl_add_u64 v[214:215], s[12:13], 0, v[196:197]
	global_load_lds_dwordx4 v[212:213], off
	v_lshl_add_u64 v[212:213], s[62:63], 0, v[198:199]
	s_add_i32 m0, s64, 0x2000
	s_nop 0
	global_load_lds_dwordx4 v[212:213], off
	v_lshl_add_u64 v[212:213], s[12:13], 0, v[192:193]
	s_mov_b32 m0, s3
	s_nop 0
	global_load_lds_dwordx4 v[212:213], off
	s_mov_b32 m0, s42
	s_nop 0
	global_load_lds_dwordx4 v[214:215], off
	s_waitcnt vmcnt(8)
	s_waitcnt lgkmcnt(0)
	s_barrier
	s_setprio 1
	s_waitcnt lgkmcnt(0)
	v_mfma_f32_16x16x32_bf16 v[60:63], v[128:131], v[160:163], v[60:63]
	v_mfma_f32_16x16x32_bf16 v[56:59], v[136:139], v[160:163], v[56:59]
	v_mfma_f32_16x16x32_bf16 v[44:47], v[128:131], v[168:171], v[44:47]
	v_mfma_f32_16x16x32_bf16 v[40:43], v[136:139], v[168:171], v[40:43]
	v_mfma_f32_16x16x32_bf16 v[28:31], v[128:131], v[176:179], v[28:31]
	v_mfma_f32_16x16x32_bf16 v[24:27], v[136:139], v[176:179], v[24:27]
	v_mfma_f32_16x16x32_bf16 v[12:15], v[128:131], v[184:187], v[12:15]
	v_mfma_f32_16x16x32_bf16 v[8:11], v[136:139], v[184:187], v[8:11]
	v_mfma_f32_16x16x32_bf16 v[60:63], v[132:135], v[164:167], v[60:63]
	v_mfma_f32_16x16x32_bf16 v[56:59], v[140:143], v[164:167], v[56:59]
	v_mfma_f32_16x16x32_bf16 v[44:47], v[132:135], v[172:175], v[44:47]
	v_mfma_f32_16x16x32_bf16 v[40:43], v[140:143], v[172:175], v[40:43]
	v_mfma_f32_16x16x32_bf16 v[28:31], v[132:135], v[180:183], v[28:31]
	v_mfma_f32_16x16x32_bf16 v[24:27], v[140:143], v[180:183], v[24:27]
	v_mfma_f32_16x16x32_bf16 v[12:15], v[132:135], v[188:191], v[12:15]
	v_mfma_f32_16x16x32_bf16 v[8:11], v[140:143], v[188:191], v[8:11]
	s_setprio 0
	s_setprio 1
	v_mfma_f32_16x16x32_bf16 v[52:55], v[144:147], v[160:163], v[52:55]
	v_mfma_f32_16x16x32_bf16 v[48:51], v[152:155], v[160:163], v[48:51]
	v_mfma_f32_16x16x32_bf16 v[36:39], v[144:147], v[168:171], v[36:39]
	v_mfma_f32_16x16x32_bf16 v[32:35], v[152:155], v[168:171], v[32:35]
	v_mfma_f32_16x16x32_bf16 v[20:23], v[144:147], v[176:179], v[20:23]
	v_mfma_f32_16x16x32_bf16 v[16:19], v[152:155], v[176:179], v[16:19]
	v_mfma_f32_16x16x32_bf16 v[4:7], v[144:147], v[184:187], v[4:7]
	v_mfma_f32_16x16x32_bf16 v[0:3], v[152:155], v[184:187], v[0:3]
	v_mfma_f32_16x16x32_bf16 v[52:55], v[148:151], v[164:167], v[52:55]
	v_mfma_f32_16x16x32_bf16 v[48:51], v[156:159], v[164:167], v[48:51]
	v_mfma_f32_16x16x32_bf16 v[36:39], v[148:151], v[172:175], v[36:39]
	v_mfma_f32_16x16x32_bf16 v[32:35], v[156:159], v[172:175], v[32:35]
	v_mfma_f32_16x16x32_bf16 v[20:23], v[148:151], v[180:183], v[20:23]
	v_mfma_f32_16x16x32_bf16 v[16:19], v[156:159], v[180:183], v[16:19]
	v_mfma_f32_16x16x32_bf16 v[4:7], v[148:151], v[188:191], v[4:7]
	v_mfma_f32_16x16x32_bf16 v[0:3], v[156:159], v[188:191], v[0:3]
	s_setprio 0
	s_barrier
	s_add_i32 s62, 0, 0x18000
	s_add_i32 s63, 0, 0x1c000
	v_add_u32_e32 v140, s62, v226
	v_add_u32_e32 v156, s63, v226
	ds_read_b128 v[128:131], v140
	ds_read_b128 v[132:135], v140 offset:1024
	ds_read_b128 v[136:139], v140 offset:2048
	ds_read_b128 v[140:143], v140 offset:3072
	ds_read_b128 v[144:147], v156
	ds_read_b128 v[148:151], v156 offset:1024
	ds_read_b128 v[152:155], v156 offset:2048
	ds_read_b128 v[156:159], v156 offset:3072
	s_add_u32 s12, s12, 0x40000
	s_addc_u32 s13, s13, 0
	s_mov_b32 m0, s43
	v_lshl_add_u64 v[216:217], s[12:13], 0, v[192:193]
	ds_read_b128 v[160:163], v229 offset:32768
	ds_read_b128 v[164:167], v229 offset:33792
	ds_read_b128 v[168:171], v229 offset:34816
	ds_read_b128 v[172:175], v229 offset:35840
	ds_read_b128 v[176:179], v229 offset:36864
	ds_read_b128 v[180:183], v229 offset:37888
	ds_read_b128 v[184:187], v229 offset:38912
	ds_read_b128 v[188:191], v229 offset:39936
	global_load_lds_dwordx4 v[216:217], off
	v_lshl_add_u64 v[216:217], s[12:13], 0, v[196:197]
	s_mov_b32 m0, s44
	s_nop 0
	global_load_lds_dwordx4 v[216:217], off
	s_waitcnt vmcnt(8)
	s_waitcnt lgkmcnt(0)
	s_barrier
	s_setprio 1
	s_waitcnt lgkmcnt(0)
	v_mfma_f32_16x16x32_bf16 v[124:127], v[128:131], v[160:163], v[124:127]
	v_mfma_f32_16x16x32_bf16 v[120:123], v[136:139], v[160:163], v[120:123]
	v_mfma_f32_16x16x32_bf16 v[108:111], v[128:131], v[168:171], v[108:111]
	v_mfma_f32_16x16x32_bf16 v[104:107], v[136:139], v[168:171], v[104:107]
	v_mfma_f32_16x16x32_bf16 v[92:95], v[128:131], v[176:179], v[92:95]
	v_mfma_f32_16x16x32_bf16 v[88:91], v[136:139], v[176:179], v[88:91]
	v_mfma_f32_16x16x32_bf16 v[76:79], v[128:131], v[184:187], v[76:79]
	v_mfma_f32_16x16x32_bf16 v[72:75], v[136:139], v[184:187], v[72:75]
	v_mfma_f32_16x16x32_bf16 v[124:127], v[132:135], v[164:167], v[124:127]
	v_mfma_f32_16x16x32_bf16 v[120:123], v[140:143], v[164:167], v[120:123]
	v_mfma_f32_16x16x32_bf16 v[108:111], v[132:135], v[172:175], v[108:111]
	v_mfma_f32_16x16x32_bf16 v[104:107], v[140:143], v[172:175], v[104:107]
	v_mfma_f32_16x16x32_bf16 v[92:95], v[132:135], v[180:183], v[92:95]
	v_mfma_f32_16x16x32_bf16 v[88:91], v[140:143], v[180:183], v[88:91]
	v_mfma_f32_16x16x32_bf16 v[76:79], v[132:135], v[188:191], v[76:79]
	v_mfma_f32_16x16x32_bf16 v[72:75], v[140:143], v[188:191], v[72:75]
	s_setprio 0
	s_setprio 1
	v_mfma_f32_16x16x32_bf16 v[116:119], v[144:147], v[160:163], v[116:119]
	v_mfma_f32_16x16x32_bf16 v[112:115], v[152:155], v[160:163], v[112:115]
	v_mfma_f32_16x16x32_bf16 v[100:103], v[144:147], v[168:171], v[100:103]
	v_mfma_f32_16x16x32_bf16 v[96:99], v[152:155], v[168:171], v[96:99]
	v_mfma_f32_16x16x32_bf16 v[84:87], v[144:147], v[176:179], v[84:87]
	v_mfma_f32_16x16x32_bf16 v[80:83], v[152:155], v[176:179], v[80:83]
	v_mfma_f32_16x16x32_bf16 v[68:71], v[144:147], v[184:187], v[68:71]
	v_mfma_f32_16x16x32_bf16 v[64:67], v[152:155], v[184:187], v[64:67]
	v_mfma_f32_16x16x32_bf16 v[116:119], v[148:151], v[164:167], v[116:119]
	v_mfma_f32_16x16x32_bf16 v[112:115], v[156:159], v[164:167], v[112:115]
	v_mfma_f32_16x16x32_bf16 v[100:103], v[148:151], v[172:175], v[100:103]
	v_mfma_f32_16x16x32_bf16 v[96:99], v[156:159], v[172:175], v[96:99]
	v_mfma_f32_16x16x32_bf16 v[84:87], v[148:151], v[180:183], v[84:87]
	v_mfma_f32_16x16x32_bf16 v[80:83], v[156:159], v[180:183], v[80:83]
	v_mfma_f32_16x16x32_bf16 v[68:71], v[148:151], v[188:191], v[68:71]
	v_mfma_f32_16x16x32_bf16 v[64:67], v[156:159], v[188:191], v[64:67]
	s_setprio 0
	s_barrier
	s_add_i32 s12, s62, s33
	v_lshl_add_u64 v[208:209], v[208:209], 0, s[16:17]
	s_mov_b32 m0, s12
	ds_read_b128 v[160:163], v229 offset:49152
	ds_read_b128 v[164:167], v229 offset:50176
	ds_read_b128 v[168:171], v229 offset:51200
	ds_read_b128 v[172:175], v229 offset:52224
	ds_read_b128 v[176:179], v229 offset:53248
	ds_read_b128 v[180:183], v229 offset:54272
	ds_read_b128 v[184:187], v229 offset:55296
	ds_read_b128 v[188:191], v229 offset:56320
	global_load_lds_dwordx4 v[208:209], off
	s_add_i32 m0, s12, 0x2000
	s_add_u32 s10, s10, 0x40080
	v_lshl_add_u64 v[208:209], v[210:211], 0, s[16:17]
	s_addc_u32 s11, s11, 0
	s_add_i32 s12, s63, s33
	global_load_lds_dwordx4 v[208:209], off
	v_lshl_add_u64 v[208:209], s[10:11], 0, v[194:195]
	s_mov_b32 m0, s12
	s_nop 0
	global_load_lds_dwordx4 v[208:209], off
	v_lshl_add_u64 v[208:209], s[10:11], 0, v[198:199]
	s_add_i32 m0, s12, 0x2000
	s_nop 0
	global_load_lds_dwordx4 v[208:209], off
	v_lshl_add_u64 v[208:209], v[212:213], 0, s[16:17]
	s_mov_b32 m0, s53
	s_nop 0
	global_load_lds_dwordx4 v[208:209], off
	v_lshl_add_u64 v[208:209], v[214:215], 0, s[16:17]
	s_mov_b32 m0, s54
	s_nop 0
	global_load_lds_dwordx4 v[208:209], off
	s_waitcnt vmcnt(8)
	s_waitcnt lgkmcnt(0)
	s_barrier
	s_setprio 1
	s_waitcnt lgkmcnt(0)
	v_mfma_f32_16x16x32_bf16 v[60:63], v[128:131], v[160:163], v[60:63]
	v_mfma_f32_16x16x32_bf16 v[56:59], v[136:139], v[160:163], v[56:59]
	v_mfma_f32_16x16x32_bf16 v[44:47], v[128:131], v[168:171], v[44:47]
	v_mfma_f32_16x16x32_bf16 v[40:43], v[136:139], v[168:171], v[40:43]
	v_mfma_f32_16x16x32_bf16 v[28:31], v[128:131], v[176:179], v[28:31]
	v_mfma_f32_16x16x32_bf16 v[24:27], v[136:139], v[176:179], v[24:27]
	v_mfma_f32_16x16x32_bf16 v[12:15], v[128:131], v[184:187], v[12:15]
	v_mfma_f32_16x16x32_bf16 v[8:11], v[136:139], v[184:187], v[8:11]
	v_mfma_f32_16x16x32_bf16 v[60:63], v[132:135], v[164:167], v[60:63]
	v_mfma_f32_16x16x32_bf16 v[56:59], v[140:143], v[164:167], v[56:59]
	v_mfma_f32_16x16x32_bf16 v[44:47], v[132:135], v[172:175], v[44:47]
	v_mfma_f32_16x16x32_bf16 v[40:43], v[140:143], v[172:175], v[40:43]
	v_mfma_f32_16x16x32_bf16 v[28:31], v[132:135], v[180:183], v[28:31]
	v_mfma_f32_16x16x32_bf16 v[24:27], v[140:143], v[180:183], v[24:27]
	v_mfma_f32_16x16x32_bf16 v[12:15], v[132:135], v[188:191], v[12:15]
	v_mfma_f32_16x16x32_bf16 v[8:11], v[140:143], v[188:191], v[8:11]
	s_setprio 0
	s_setprio 1
	v_mfma_f32_16x16x32_bf16 v[52:55], v[144:147], v[160:163], v[52:55]
	v_mfma_f32_16x16x32_bf16 v[48:51], v[152:155], v[160:163], v[48:51]
	v_mfma_f32_16x16x32_bf16 v[36:39], v[144:147], v[168:171], v[36:39]
	v_mfma_f32_16x16x32_bf16 v[32:35], v[152:155], v[168:171], v[32:35]
	v_mfma_f32_16x16x32_bf16 v[20:23], v[144:147], v[176:179], v[20:23]
	v_mfma_f32_16x16x32_bf16 v[16:19], v[152:155], v[176:179], v[16:19]
	v_mfma_f32_16x16x32_bf16 v[4:7], v[144:147], v[184:187], v[4:7]
	v_mfma_f32_16x16x32_bf16 v[0:3], v[152:155], v[184:187], v[0:3]
	v_mfma_f32_16x16x32_bf16 v[52:55], v[148:151], v[164:167], v[52:55]
	v_mfma_f32_16x16x32_bf16 v[48:51], v[156:159], v[164:167], v[48:51]
	v_mfma_f32_16x16x32_bf16 v[36:39], v[148:151], v[172:175], v[36:39]
	v_mfma_f32_16x16x32_bf16 v[32:35], v[156:159], v[172:175], v[32:35]
	v_mfma_f32_16x16x32_bf16 v[20:23], v[148:151], v[180:183], v[20:23]
	v_mfma_f32_16x16x32_bf16 v[16:19], v[156:159], v[180:183], v[16:19]
	v_mfma_f32_16x16x32_bf16 v[4:7], v[148:151], v[188:191], v[4:7]
	v_mfma_f32_16x16x32_bf16 v[0:3], v[156:159], v[188:191], v[0:3]
	s_setprio 0
	s_add_i32 s61, s61, 2
	s_add_u32 s8, s8, 0x100
	s_addc_u32 s9, s9, 0
	s_add_u32 s59, s59, 0x100
	s_addc_u32 s60, s60, 0
	s_cmp_gt_u32 s61, 13
	s_barrier
	s_cbranch_scc0 .LBB0_606
	s_and_b64 vcc, exec, s[18:19]
	s_cbranch_vccz .LBB0_609
	s_barrier

.LBB0_740:
	ds_read_b128 v[44:47], v205
	ds_read_b128 v[48:51], v205 offset:1024
	ds_read_b128 v[52:55], v205 offset:2048
	ds_read_b128 v[56:59], v205 offset:3072
	ds_read_b128 v[60:63], v206
	ds_read_b128 v[64:67], v206 offset:1024
	ds_read_b128 v[68:71], v206 offset:2048
	ds_read_b128 v[160:163], v206 offset:3072
	s_add_u32 s12, s10, s8
	s_addc_u32 s13, s11, s9
	s_add_u32 s12, s12, 0x100
	s_addc_u32 s13, s13, 0
	s_add_u32 s63, s19, s8
	s_addc_u32 vcc_lo, s55, s9
	s_cmpk_eq_i32 s8, 0x700
	s_cselect_b32 s15, s59, s13
	s_cselect_b32 s14, s58, s12
	s_cselect_b32 s4, s57, s1
	s_cselect_b32 s5, s56, s0
	s_cselect_b32 s13, s3, vcc_lo
	s_cselect_b32 s12, s18, s63
	s_cselect_b32 s63, s97, s17
	v_lshl_add_u64 v[224:225], v[42:43], 0, s[8:9]
	s_add_i32 m0, s65, 0xc000
	ds_read_b128 v[164:167], v207
	ds_read_b128 v[168:171], v207 offset:1024
	ds_read_b128 v[172:175], v207 offset:2048
	ds_read_b128 v[194:197], v207 offset:3072
	ds_read_b128 v[198:201], v207 offset:4096
	ds_read_b128 v[210:213], v207 offset:5120
	ds_read_b128 v[214:217], v207 offset:6144
	ds_read_b128 v[218:221], v207 offset:7168
	global_load_lds_dwordx4 v[224:225], off
	v_lshl_add_u64 v[224:225], v[40:41], 0, s[8:9]
	s_add_i32 m0, s65, 0xe000
	s_nop 0
	global_load_lds_dwordx4 v[224:225], off
	s_waitcnt vmcnt(8)
	s_waitcnt lgkmcnt(0)
	s_barrier
	s_setprio 1
	s_waitcnt lgkmcnt(0)
	v_mfma_f32_16x16x32_bf16 v[156:159], v[44:47], v[164:167], v[156:159]
	v_mfma_f32_16x16x32_bf16 v[152:155], v[52:55], v[164:167], v[152:155]
	v_mfma_f32_16x16x32_bf16 v[140:143], v[44:47], v[172:175], v[140:143]
	v_mfma_f32_16x16x32_bf16 v[136:139], v[52:55], v[172:175], v[136:139]
	v_mfma_f32_16x16x32_bf16 v[124:127], v[44:47], v[198:201], v[124:127]
	v_mfma_f32_16x16x32_bf16 v[120:123], v[52:55], v[198:201], v[120:123]
	v_readlane_b32 s32, v247, 60
	v_mfma_f32_16x16x32_bf16 v[108:111], v[44:47], v[214:217], v[108:111]
	s_add_i32 s32, s32, -1
	v_readlane_b32 s100, v247, 61
	v_mfma_f32_16x16x32_bf16 v[104:107], v[52:55], v[214:217], v[104:107]
	s_min_u32 s32, s32, s100
	v_readlane_b32 s100, v247, 62
	v_mfma_f32_16x16x32_bf16 v[156:159], v[48:51], v[168:171], v[156:159]
	s_add_i32 s32, s32, s100
	s_min_u32 s32, s32, 0x2f6f
	v_mfma_f32_16x16x32_bf16 v[152:155], v[56:59], v[168:171], v[152:155]
	s_lshr_b32 s100, s32, 1
	s_add_i32 s100, s100, 0x2808
	v_mfma_f32_16x16x32_bf16 v[140:143], v[48:51], v[194:197], v[140:143]
	s_mul_i32 s101, s100, 0x8081
	s_lshr_b32 s101, s101, 24
	v_mfma_f32_16x16x32_bf16 v[136:139], v[56:59], v[194:197], v[136:139]
	s_mul_i32 s98, s101, 0x1fe
	s_sub_i32 s100, s100, s98
	v_mfma_f32_16x16x32_bf16 v[124:127], v[48:51], v[210:213], v[124:127]
	s_lshl_b32 s101, s101, 22
	s_lshl_b32 s100, s100, 13
	v_mfma_f32_16x16x32_bf16 v[120:123], v[56:59], v[210:213], v[120:123]
	s_add_u32 s100, s100, s101
	s_bitcmp1_b32 s32, 0
	v_mfma_f32_16x16x32_bf16 v[108:111], v[48:51], v[218:221], v[108:111]
	s_cselect_b32 s98, s66, s70
	s_cselect_b32 s99, s67, s71
	v_mfma_f32_16x16x32_bf16 v[104:107], v[56:59], v[218:221], v[104:107]
	s_add_u32 s98, s98, s100
	s_addc_u32 s99, s99, 0
	s_setprio 0
	s_setprio 1
	v_mfma_f32_16x16x32_bf16 v[148:151], v[60:63], v[164:167], v[148:151]
	v_lshlrev_b32_e32 v236, 4, v222
	global_store_dwordx4 v236, v[252:255], s[98:99] nt
	v_mfma_f32_16x16x32_bf16 v[144:147], v[68:71], v[164:167], v[144:147]
	v_readlane_b32 s32, v247, 60
	v_readlane_b32 s100, v247, 61
	v_mfma_f32_16x16x32_bf16 v[132:135], v[60:63], v[172:175], v[132:135]
	s_min_u32 s32, s32, s100
	v_readlane_b32 s100, v247, 62
	v_mfma_f32_16x16x32_bf16 v[128:131], v[68:71], v[172:175], v[128:131]
	s_add_i32 s32, s32, s100
	s_min_u32 s32, s32, 0x2f6f
	v_mfma_f32_16x16x32_bf16 v[116:119], v[60:63], v[198:201], v[116:119]
	s_lshr_b32 s100, s32, 1
	s_add_i32 s100, s100, 0x2808
	v_mfma_f32_16x16x32_bf16 v[112:115], v[68:71], v[198:201], v[112:115]
	s_mul_i32 s101, s100, 0x8081
	s_lshr_b32 s101, s101, 24
	v_mfma_f32_16x16x32_bf16 v[100:103], v[60:63], v[214:217], v[100:103]
	s_mul_i32 s98, s101, 0x1fe
	s_sub_i32 s100, s100, s98
	v_mfma_f32_16x16x32_bf16 v[96:99], v[68:71], v[214:217], v[96:99]
	s_lshl_b32 s101, s101, 22
	s_lshl_b32 s100, s100, 13
	v_mfma_f32_16x16x32_bf16 v[148:151], v[64:67], v[168:171], v[148:151]
	s_add_u32 s100, s100, s101
	s_bitcmp1_b32 s32, 0
	v_mfma_f32_16x16x32_bf16 v[144:147], v[160:163], v[168:171], v[144:147]
	s_cselect_b32 s98, s84, s82
	s_cselect_b32 s99, s85, s83
	v_mfma_f32_16x16x32_bf16 v[132:135], v[64:67], v[194:197], v[132:135]
	s_add_u32 s98, s98, s100
	s_addc_u32 s99, s99, 0
	v_mfma_f32_16x16x32_bf16 v[128:131], v[160:163], v[194:197], v[128:131]
	s_add_u32 s98, s98, 0x4000
	s_addc_u32 s99, s99, 0
	v_mfma_f32_16x16x32_bf16 v[116:119], v[64:67], v[210:213], v[116:119]
	v_lshlrev_b32_e32 v236, 4, v222
	global_load_dwordx4 v[252:255], v236, s[98:99] nt
	v_mfma_f32_16x16x32_bf16 v[112:115], v[160:163], v[210:213], v[112:115]
	v_readlane_b32 s32, v247, 60
	s_add_i32 s32, s32, 1
	v_mfma_f32_16x16x32_bf16 v[100:103], v[64:67], v[218:221], v[100:103]
	v_writelane_b32 v247, s32, 60
	s_nop 0
	v_mfma_f32_16x16x32_bf16 v[96:99], v[160:163], v[218:221], v[96:99]
	s_setprio 0
	s_barrier
	s_add_i32 vcc_lo, s88, s33
	v_lshl_add_u64 v[228:229], s[12:13], 0, v[178:179]
	s_mov_b32 m0, vcc_lo
	ds_read_b128 v[164:167], v207 offset:16384
	ds_read_b128 v[168:171], v207 offset:17408
	ds_read_b128 v[172:175], v207 offset:18432
	ds_read_b128 v[194:197], v207 offset:19456
	ds_read_b128 v[198:201], v207 offset:20480
	ds_read_b128 v[210:213], v207 offset:21504
	ds_read_b128 v[214:217], v207 offset:22528
	ds_read_b128 v[218:221], v207 offset:23552
	global_load_lds_dwordx4 v[228:229], off
	s_add_i32 m0, vcc_lo, 0x2000
	s_add_u32 vcc_lo, s12, 0x40000
	v_lshl_add_u64 v[230:231], s[12:13], 0, v[182:183]
	s_addc_u32 vcc_hi, s13, 0
	s_add_i32 s36, s89, s33
	global_load_lds_dwordx4 v[230:231], off
	v_lshl_add_u64 v[224:225], vcc, 0, v[178:179]
	s_mov_b32 m0, s36
	v_lshl_add_u64 v[232:233], s[14:15], 0, v[176:177]
	global_load_lds_dwordx4 v[224:225], off
	s_add_i32 m0, s36, 0x2000
	v_lshl_add_u64 v[224:225], vcc, 0, v[182:183]
	s_sub_u32 vcc_lo, 0, s63
	global_load_lds_dwordx4 v[224:225], off
	s_mov_b32 m0, s65
	v_lshl_add_u64 v[224:225], s[14:15], 0, v[180:181]
	s_subb_u32 vcc_hi, 0, 0
	global_load_lds_dwordx4 v[232:233], off
	v_lshl_add_u64 v[234:235], v[224:225], 0, vcc
	s_mov_b32 m0, s68
	s_nop 0
	global_load_lds_dwordx4 v[234:235], off
	s_waitcnt vmcnt(10)
	s_waitcnt lgkmcnt(0)
	s_barrier
	s_setprio 1
	s_waitcnt lgkmcnt(0)
	v_mfma_f32_16x16x32_bf16 v[92:95], v[44:47], v[164:167], v[92:95]
	v_mfma_f32_16x16x32_bf16 v[88:91], v[52:55], v[164:167], v[88:91]
	v_mfma_f32_16x16x32_bf16 v[76:79], v[44:47], v[172:175], v[76:79]
	v_mfma_f32_16x16x32_bf16 v[72:75], v[52:55], v[172:175], v[72:75]
	v_mfma_f32_16x16x32_bf16 v[28:31], v[44:47], v[198:201], v[28:31]
	v_mfma_f32_16x16x32_bf16 v[24:27], v[52:55], v[198:201], v[24:27]
	v_mfma_f32_16x16x32_bf16 v[12:15], v[44:47], v[214:217], v[12:15]
	v_mfma_f32_16x16x32_bf16 v[8:11], v[52:55], v[214:217], v[8:11]
	v_mfma_f32_16x16x32_bf16 v[92:95], v[48:51], v[168:171], v[92:95]
	v_mfma_f32_16x16x32_bf16 v[88:91], v[56:59], v[168:171], v[88:91]
	v_mfma_f32_16x16x32_bf16 v[76:79], v[48:51], v[194:197], v[76:79]
	v_mfma_f32_16x16x32_bf16 v[72:75], v[56:59], v[194:197], v[72:75]
	v_mfma_f32_16x16x32_bf16 v[28:31], v[48:51], v[210:213], v[28:31]
	v_mfma_f32_16x16x32_bf16 v[24:27], v[56:59], v[210:213], v[24:27]
	v_mfma_f32_16x16x32_bf16 v[12:15], v[48:51], v[218:221], v[12:15]
	v_mfma_f32_16x16x32_bf16 v[8:11], v[56:59], v[218:221], v[8:11]
	s_setprio 0
	s_setprio 1
	v_mfma_f32_16x16x32_bf16 v[36:39], v[60:63], v[172:175], v[36:39]
	v_mfma_f32_16x16x32_bf16 v[32:35], v[68:71], v[172:175], v[32:35]
	v_mfma_f32_16x16x32_bf16 v[20:23], v[60:63], v[198:201], v[20:23]
	v_mfma_f32_16x16x32_bf16 v[16:19], v[68:71], v[198:201], v[16:19]
	v_mfma_f32_16x16x32_bf16 v[4:7], v[60:63], v[214:217], v[4:7]
	v_mfma_f32_16x16x32_bf16 v[0:3], v[68:71], v[214:217], v[0:3]
	v_mfma_f32_16x16x32_bf16 v[44:47], v[60:63], v[164:167], v[84:87]
	v_mfma_f32_16x16x32_bf16 v[48:51], v[68:71], v[164:167], v[80:83]
	v_mfma_f32_16x16x32_bf16 v[36:39], v[64:67], v[194:197], v[36:39]
	v_mfma_f32_16x16x32_bf16 v[32:35], v[160:163], v[194:197], v[32:35]
	v_mfma_f32_16x16x32_bf16 v[20:23], v[64:67], v[210:213], v[20:23]
	v_mfma_f32_16x16x32_bf16 v[16:19], v[160:163], v[210:213], v[16:19]
	v_mfma_f32_16x16x32_bf16 v[4:7], v[64:67], v[218:221], v[4:7]
	v_mfma_f32_16x16x32_bf16 v[0:3], v[160:163], v[218:221], v[0:3]
	v_mfma_f32_16x16x32_bf16 v[44:47], v[64:67], v[168:171], v[44:47]
	v_mfma_f32_16x16x32_bf16 v[48:51], v[160:163], v[168:171], v[48:51]
	s_setprio 0
	s_barrier
	s_add_i32 s36, 0, 0x18000
	s_add_i32 s37, 0, 0x1c000
	v_add_u32_e32 v64, s36, v204
	v_add_u32_e32 v80, s37, v204
	ds_read_b128 v[52:55], v64
	ds_read_b128 v[56:59], v64 offset:1024
	ds_read_b128 v[60:63], v64 offset:2048
	ds_read_b128 v[64:67], v64 offset:3072
	ds_read_b128 v[68:71], v80
	ds_read_b128 v[160:163], v80 offset:1024
	ds_read_b128 v[164:167], v80 offset:2048
	ds_read_b128 v[168:171], v80 offset:3072
	s_add_u32 s14, s14, s5
	s_addc_u32 s15, s15, s4
	s_mov_b32 m0, s69
	v_lshl_add_u64 v[224:225], s[14:15], 0, v[176:177]
	ds_read_b128 v[80:83], v207 offset:32768
	ds_read_b128 v[84:87], v207 offset:33792
	ds_read_b128 v[172:175], v207 offset:34816
	ds_read_b128 v[194:197], v207 offset:35840
	ds_read_b128 v[198:201], v207 offset:36864
	ds_read_b128 v[210:213], v207 offset:37888
	ds_read_b128 v[214:217], v207 offset:38912
	ds_read_b128 v[218:221], v207 offset:39936
	global_load_lds_dwordx4 v[224:225], off
	v_lshl_add_u64 v[224:225], s[14:15], 0, v[180:181]
	v_lshl_add_u64 v[224:225], v[224:225], 0, vcc
	s_mov_b32 m0, s72
	s_nop 0
	global_load_lds_dwordx4 v[224:225], off
	s_waitcnt vmcnt(10)
	s_waitcnt lgkmcnt(0)
	s_barrier
	s_setprio 1
	s_waitcnt lgkmcnt(0)
	v_mfma_f32_16x16x32_bf16 v[156:159], v[52:55], v[80:83], v[156:159]
	v_mfma_f32_16x16x32_bf16 v[152:155], v[60:63], v[80:83], v[152:155]
	v_mfma_f32_16x16x32_bf16 v[140:143], v[52:55], v[172:175], v[140:143]
	v_mfma_f32_16x16x32_bf16 v[136:139], v[60:63], v[172:175], v[136:139]
	v_mfma_f32_16x16x32_bf16 v[124:127], v[52:55], v[198:201], v[124:127]
	v_mfma_f32_16x16x32_bf16 v[120:123], v[60:63], v[198:201], v[120:123]
	v_mfma_f32_16x16x32_bf16 v[108:111], v[52:55], v[214:217], v[108:111]
	v_mfma_f32_16x16x32_bf16 v[104:107], v[60:63], v[214:217], v[104:107]
	v_mfma_f32_16x16x32_bf16 v[156:159], v[56:59], v[84:87], v[156:159]
	v_mfma_f32_16x16x32_bf16 v[152:155], v[64:67], v[84:87], v[152:155]
	v_mfma_f32_16x16x32_bf16 v[140:143], v[56:59], v[194:197], v[140:143]
	v_mfma_f32_16x16x32_bf16 v[136:139], v[64:67], v[194:197], v[136:139]
	v_mfma_f32_16x16x32_bf16 v[124:127], v[56:59], v[210:213], v[124:127]
	v_mfma_f32_16x16x32_bf16 v[120:123], v[64:67], v[210:213], v[120:123]
	v_mfma_f32_16x16x32_bf16 v[108:111], v[56:59], v[218:221], v[108:111]
	v_mfma_f32_16x16x32_bf16 v[104:107], v[64:67], v[218:221], v[104:107]
	s_setprio 0
	s_setprio 1
	v_mfma_f32_16x16x32_bf16 v[148:151], v[68:71], v[80:83], v[148:151]
	v_mfma_f32_16x16x32_bf16 v[80:83], v[164:167], v[80:83], v[144:147]
	v_mfma_f32_16x16x32_bf16 v[144:147], v[168:171], v[84:87], v[80:83]
	v_mfma_f32_16x16x32_bf16 v[80:83], v[68:71], v[172:175], v[132:135]
	v_mfma_f32_16x16x32_bf16 v[132:135], v[160:163], v[194:197], v[80:83]
	v_mfma_f32_16x16x32_bf16 v[80:83], v[164:167], v[172:175], v[128:131]
	v_mfma_f32_16x16x32_bf16 v[128:131], v[168:171], v[194:197], v[80:83]
	v_mfma_f32_16x16x32_bf16 v[80:83], v[68:71], v[198:201], v[116:119]
	v_mfma_f32_16x16x32_bf16 v[116:119], v[160:163], v[210:213], v[80:83]
	v_mfma_f32_16x16x32_bf16 v[80:83], v[164:167], v[198:201], v[112:115]
	v_mfma_f32_16x16x32_bf16 v[112:115], v[168:171], v[210:213], v[80:83]
	v_mfma_f32_16x16x32_bf16 v[80:83], v[68:71], v[214:217], v[100:103]
	v_mfma_f32_16x16x32_bf16 v[100:103], v[160:163], v[218:221], v[80:83]
	v_mfma_f32_16x16x32_bf16 v[80:83], v[164:167], v[214:217], v[96:99]
	v_mfma_f32_16x16x32_bf16 v[148:151], v[160:163], v[84:87], v[148:151]
	v_mfma_f32_16x16x32_bf16 v[96:99], v[168:171], v[218:221], v[80:83]
	s_setprio 0
	s_barrier
	s_add_i32 s4, s36, s33
	v_lshl_add_u64 v[84:85], v[228:229], 0, s[50:51]
	s_mov_b32 m0, s4
	s_nop 0
	ds_read_b128 v[80:83], v207 offset:49152
	ds_read_b128 v[172:175], v207 offset:50176
	ds_read_b128 v[194:197], v207 offset:51200
	ds_read_b128 v[198:201], v207 offset:52224
	ds_read_b128 v[210:213], v207 offset:53248
	ds_read_b128 v[214:217], v207 offset:54272
	ds_read_b128 v[218:221], v207 offset:55296
	ds_read_b128 v[224:227], v207 offset:56320
	global_load_lds_dwordx4 v[84:85], off
	s_add_i32 m0, s4, 0x2000
	s_add_u32 s12, s12, 0x40080
	v_lshl_add_u64 v[84:85], v[230:231], 0, s[50:51]
	s_addc_u32 s13, s13, 0
	s_add_i32 s4, s37, s33
	global_load_lds_dwordx4 v[84:85], off
	v_lshl_add_u64 v[84:85], s[12:13], 0, v[178:179]
	s_mov_b32 m0, s4
	s_nop 0
	global_load_lds_dwordx4 v[84:85], off
	v_lshl_add_u64 v[84:85], s[12:13], 0, v[182:183]
	s_add_i32 m0, s4, 0x2000
	s_nop 0
	global_load_lds_dwordx4 v[84:85], off
	v_lshl_add_u64 v[84:85], v[232:233], 0, s[50:51]
	s_mov_b32 m0, s75
	s_nop 0
	global_load_lds_dwordx4 v[84:85], off
	v_lshl_add_u64 v[84:85], v[234:235], 0, s[50:51]
	s_mov_b32 m0, s76
	s_nop 0
	global_load_lds_dwordx4 v[84:85], off
	s_waitcnt vmcnt(8)
	s_waitcnt lgkmcnt(0)
	s_barrier
	s_setprio 1
	s_waitcnt lgkmcnt(0)
	v_mfma_f32_16x16x32_bf16 v[84:87], v[52:55], v[80:83], v[92:95]
	v_mfma_f32_16x16x32_bf16 v[92:95], v[56:59], v[172:175], v[84:87]
	v_mfma_f32_16x16x32_bf16 v[84:87], v[60:63], v[80:83], v[88:91]
	v_mfma_f32_16x16x32_bf16 v[76:79], v[52:55], v[194:197], v[76:79]
	v_mfma_f32_16x16x32_bf16 v[72:75], v[60:63], v[194:197], v[72:75]
	v_mfma_f32_16x16x32_bf16 v[28:31], v[52:55], v[210:213], v[28:31]
	v_mfma_f32_16x16x32_bf16 v[24:27], v[60:63], v[210:213], v[24:27]
	v_mfma_f32_16x16x32_bf16 v[12:15], v[52:55], v[218:221], v[12:15]
	v_mfma_f32_16x16x32_bf16 v[8:11], v[60:63], v[218:221], v[8:11]
	v_mfma_f32_16x16x32_bf16 v[88:91], v[64:67], v[172:175], v[84:87]
	v_mfma_f32_16x16x32_bf16 v[76:79], v[56:59], v[198:201], v[76:79]
	v_mfma_f32_16x16x32_bf16 v[72:75], v[64:67], v[198:201], v[72:75]
	v_mfma_f32_16x16x32_bf16 v[28:31], v[56:59], v[214:217], v[28:31]
	v_mfma_f32_16x16x32_bf16 v[24:27], v[64:67], v[214:217], v[24:27]
	v_mfma_f32_16x16x32_bf16 v[12:15], v[56:59], v[224:227], v[12:15]
	v_mfma_f32_16x16x32_bf16 v[8:11], v[64:67], v[224:227], v[8:11]
	s_setprio 0
	s_setprio 1
	v_mfma_f32_16x16x32_bf16 v[44:47], v[68:71], v[80:83], v[44:47]
	v_mfma_f32_16x16x32_bf16 v[84:87], v[160:163], v[172:175], v[44:47]
	v_mfma_f32_16x16x32_bf16 v[44:47], v[164:167], v[80:83], v[48:51]
	v_mfma_f32_16x16x32_bf16 v[36:39], v[68:71], v[194:197], v[36:39]
	v_mfma_f32_16x16x32_bf16 v[32:35], v[164:167], v[194:197], v[32:35]
	v_mfma_f32_16x16x32_bf16 v[20:23], v[68:71], v[210:213], v[20:23]
	v_mfma_f32_16x16x32_bf16 v[16:19], v[164:167], v[210:213], v[16:19]
	v_mfma_f32_16x16x32_bf16 v[4:7], v[68:71], v[218:221], v[4:7]
	v_mfma_f32_16x16x32_bf16 v[0:3], v[164:167], v[218:221], v[0:3]
	v_mfma_f32_16x16x32_bf16 v[80:83], v[168:171], v[172:175], v[44:47]
	v_mfma_f32_16x16x32_bf16 v[36:39], v[160:163], v[198:201], v[36:39]
	v_mfma_f32_16x16x32_bf16 v[32:35], v[168:171], v[198:201], v[32:35]
	v_mfma_f32_16x16x32_bf16 v[20:23], v[160:163], v[214:217], v[20:23]
	v_mfma_f32_16x16x32_bf16 v[16:19], v[168:171], v[214:217], v[16:19]
	v_mfma_f32_16x16x32_bf16 v[4:7], v[160:163], v[224:227], v[4:7]
	v_mfma_f32_16x16x32_bf16 v[0:3], v[168:171], v[224:227], v[0:3]
	s_setprio 0
	s_add_i32 s62, s62, 2
	s_add_u32 s8, s8, 0x100
	s_addc_u32 s9, s9, 0
	s_cmp_gt_u32 s62, 13
	s_barrier
	s_cbranch_scc0 .LBB0_740
	s_and_b64 vcc, exec, s[52:53]
	s_cbranch_vccz .LBB0_743
	s_barrier

.LBB0_1044:
	ds_read_b128 v[128:131], v230
	ds_read_b128 v[132:135], v230 offset:1024
	ds_read_b128 v[136:139], v230 offset:2048
	ds_read_b128 v[140:143], v230 offset:3072
	ds_read_b128 v[144:147], v231
	ds_read_b128 v[148:151], v231 offset:1024
	ds_read_b128 v[152:155], v231 offset:2048
	ds_read_b128 v[156:159], v231 offset:3072
	s_add_u32 s24, s2, 0x100
	s_addc_u32 s25, s3, 0
	s_cmp_eq_u32 s61, s101
	s_cselect_b32 s35, s7, s25
	s_cselect_b32 s34, s6, s24
	s_cselect_b32 s27, s19, s60
	s_cselect_b32 s26, s18, s59
	v_lshl_add_u64 v[208:209], s[2:3], 0, v[200:201]
	s_add_i32 m0, s36, 0xc000
	ds_read_b128 v[160:163], v232
	ds_read_b128 v[164:167], v232 offset:1024
	ds_read_b128 v[168:171], v232 offset:2048
	ds_read_b128 v[172:175], v232 offset:3072
	ds_read_b128 v[176:179], v232 offset:4096
	ds_read_b128 v[180:183], v232 offset:5120
	ds_read_b128 v[184:187], v232 offset:6144
	ds_read_b128 v[188:191], v232 offset:7168
	global_load_lds_dwordx4 v[208:209], off
	v_lshl_add_u64 v[208:209], s[2:3], 0, v[202:203]
	s_add_i32 m0, s36, 0xe000
	s_nop 0
	global_load_lds_dwordx4 v[208:209], off
	s_waitcnt vmcnt(8)
	s_waitcnt lgkmcnt(0)
	s_barrier
	s_setprio 1
	s_waitcnt lgkmcnt(0)
	v_mfma_f32_16x16x32_bf16 v[124:127], v[128:131], v[160:163], v[124:127]
	v_mfma_f32_16x16x32_bf16 v[120:123], v[136:139], v[160:163], v[120:123]
	v_mfma_f32_16x16x32_bf16 v[108:111], v[128:131], v[168:171], v[108:111]
	v_mfma_f32_16x16x32_bf16 v[104:107], v[136:139], v[168:171], v[104:107]
	v_mfma_f32_16x16x32_bf16 v[92:95], v[128:131], v[176:179], v[92:95]
	v_mfma_f32_16x16x32_bf16 v[88:91], v[136:139], v[176:179], v[88:91]
	v_mfma_f32_16x16x32_bf16 v[76:79], v[128:131], v[184:187], v[76:79]
	v_mfma_f32_16x16x32_bf16 v[72:75], v[136:139], v[184:187], v[72:75]
	v_mfma_f32_16x16x32_bf16 v[124:127], v[132:135], v[164:167], v[124:127]
	v_mfma_f32_16x16x32_bf16 v[120:123], v[140:143], v[164:167], v[120:123]
	v_mfma_f32_16x16x32_bf16 v[108:111], v[132:135], v[172:175], v[108:111]
	v_mfma_f32_16x16x32_bf16 v[104:107], v[140:143], v[172:175], v[104:107]
	v_mfma_f32_16x16x32_bf16 v[92:95], v[132:135], v[180:183], v[92:95]
	v_mfma_f32_16x16x32_bf16 v[88:91], v[140:143], v[180:183], v[88:91]
	v_mfma_f32_16x16x32_bf16 v[76:79], v[132:135], v[188:191], v[76:79]
	v_mfma_f32_16x16x32_bf16 v[72:75], v[140:143], v[188:191], v[72:75]
	s_setprio 0
	s_setprio 1
	v_mfma_f32_16x16x32_bf16 v[116:119], v[144:147], v[160:163], v[116:119]
	v_mfma_f32_16x16x32_bf16 v[112:115], v[152:155], v[160:163], v[112:115]
	v_mfma_f32_16x16x32_bf16 v[100:103], v[144:147], v[168:171], v[100:103]
	v_mfma_f32_16x16x32_bf16 v[96:99], v[152:155], v[168:171], v[96:99]
	v_mfma_f32_16x16x32_bf16 v[84:87], v[144:147], v[176:179], v[84:87]
	v_mfma_f32_16x16x32_bf16 v[80:83], v[152:155], v[176:179], v[80:83]
	v_mfma_f32_16x16x32_bf16 v[68:71], v[144:147], v[184:187], v[68:71]
	v_mfma_f32_16x16x32_bf16 v[64:67], v[152:155], v[184:187], v[64:67]
	v_mfma_f32_16x16x32_bf16 v[116:119], v[148:151], v[164:167], v[116:119]
	v_mfma_f32_16x16x32_bf16 v[112:115], v[156:159], v[164:167], v[112:115]
	v_mfma_f32_16x16x32_bf16 v[100:103], v[148:151], v[172:175], v[100:103]
	v_mfma_f32_16x16x32_bf16 v[96:99], v[156:159], v[172:175], v[96:99]
	v_mfma_f32_16x16x32_bf16 v[84:87], v[148:151], v[180:183], v[84:87]
	v_mfma_f32_16x16x32_bf16 v[80:83], v[156:159], v[180:183], v[80:83]
	v_mfma_f32_16x16x32_bf16 v[68:71], v[148:151], v[188:191], v[68:71]
	v_mfma_f32_16x16x32_bf16 v[64:67], v[156:159], v[188:191], v[64:67]
	s_setprio 0
	s_barrier
	s_add_i32 s2, s49, s33
	v_lshl_add_u64 v[208:209], s[26:27], 0, v[194:195]
	s_mov_b32 m0, s2
	ds_read_b128 v[160:163], v232 offset:16384
	ds_read_b128 v[164:167], v232 offset:17408
	ds_read_b128 v[168:171], v232 offset:18432
	ds_read_b128 v[172:175], v232 offset:19456
	ds_read_b128 v[176:179], v232 offset:20480
	ds_read_b128 v[180:183], v232 offset:21504
	ds_read_b128 v[184:187], v232 offset:22528
	ds_read_b128 v[188:191], v232 offset:23552
	global_load_lds_dwordx4 v[208:209], off
	s_add_i32 m0, s2, 0x2000
	s_add_u32 s2, s26, 0xb0000
	v_lshl_add_u64 v[210:211], s[26:27], 0, v[198:199]
	s_addc_u32 s3, s27, 0
	s_add_i32 s62, s50, s33
	global_load_lds_dwordx4 v[210:211], off
	v_lshl_add_u64 v[212:213], s[2:3], 0, v[194:195]
	s_mov_b32 m0, s62
	v_lshl_add_u64 v[214:215], s[34:35], 0, v[196:197]
	global_load_lds_dwordx4 v[212:213], off
	v_lshl_add_u64 v[212:213], s[2:3], 0, v[198:199]
	s_add_i32 m0, s62, 0x2000
	s_nop 0
	global_load_lds_dwordx4 v[212:213], off
	v_lshl_add_u64 v[212:213], s[34:35], 0, v[192:193]
	s_mov_b32 m0, s36
	s_nop 0
	global_load_lds_dwordx4 v[212:213], off
	s_mov_b32 m0, s37
	s_nop 0
	global_load_lds_dwordx4 v[214:215], off
	s_waitcnt vmcnt(8)
	s_waitcnt lgkmcnt(0)
	s_barrier
	s_setprio 1
	s_waitcnt lgkmcnt(0)
	v_mfma_f32_16x16x32_bf16 v[60:63], v[128:131], v[160:163], v[60:63]
	v_mfma_f32_16x16x32_bf16 v[56:59], v[136:139], v[160:163], v[56:59]
	v_mfma_f32_16x16x32_bf16 v[44:47], v[128:131], v[168:171], v[44:47]
	v_mfma_f32_16x16x32_bf16 v[40:43], v[136:139], v[168:171], v[40:43]
	v_mfma_f32_16x16x32_bf16 v[28:31], v[128:131], v[176:179], v[28:31]
	v_mfma_f32_16x16x32_bf16 v[24:27], v[136:139], v[176:179], v[24:27]
	v_mfma_f32_16x16x32_bf16 v[12:15], v[128:131], v[184:187], v[12:15]
	v_mfma_f32_16x16x32_bf16 v[8:11], v[136:139], v[184:187], v[8:11]
	v_mfma_f32_16x16x32_bf16 v[60:63], v[132:135], v[164:167], v[60:63]
	v_mfma_f32_16x16x32_bf16 v[56:59], v[140:143], v[164:167], v[56:59]
	v_mfma_f32_16x16x32_bf16 v[44:47], v[132:135], v[172:175], v[44:47]
	v_mfma_f32_16x16x32_bf16 v[40:43], v[140:143], v[172:175], v[40:43]
	v_mfma_f32_16x16x32_bf16 v[28:31], v[132:135], v[180:183], v[28:31]
	v_mfma_f32_16x16x32_bf16 v[24:27], v[140:143], v[180:183], v[24:27]
	v_mfma_f32_16x16x32_bf16 v[12:15], v[132:135], v[188:191], v[12:15]
	v_mfma_f32_16x16x32_bf16 v[8:11], v[140:143], v[188:191], v[8:11]
	s_setprio 0
	s_setprio 1
	v_mfma_f32_16x16x32_bf16 v[52:55], v[144:147], v[160:163], v[52:55]
	v_mfma_f32_16x16x32_bf16 v[48:51], v[152:155], v[160:163], v[48:51]
	v_mfma_f32_16x16x32_bf16 v[36:39], v[144:147], v[168:171], v[36:39]
	v_mfma_f32_16x16x32_bf16 v[32:35], v[152:155], v[168:171], v[32:35]
	v_mfma_f32_16x16x32_bf16 v[20:23], v[144:147], v[176:179], v[20:23]
	v_mfma_f32_16x16x32_bf16 v[16:19], v[152:155], v[176:179], v[16:19]
	v_mfma_f32_16x16x32_bf16 v[4:7], v[144:147], v[184:187], v[4:7]
	v_mfma_f32_16x16x32_bf16 v[0:3], v[152:155], v[184:187], v[0:3]
	v_mfma_f32_16x16x32_bf16 v[52:55], v[148:151], v[164:167], v[52:55]
	v_mfma_f32_16x16x32_bf16 v[48:51], v[156:159], v[164:167], v[48:51]
	v_mfma_f32_16x16x32_bf16 v[36:39], v[148:151], v[172:175], v[36:39]
	v_mfma_f32_16x16x32_bf16 v[32:35], v[156:159], v[172:175], v[32:35]
	v_mfma_f32_16x16x32_bf16 v[20:23], v[148:151], v[180:183], v[20:23]
	v_mfma_f32_16x16x32_bf16 v[16:19], v[156:159], v[180:183], v[16:19]
	v_mfma_f32_16x16x32_bf16 v[4:7], v[148:151], v[188:191], v[4:7]
	v_mfma_f32_16x16x32_bf16 v[0:3], v[156:159], v[188:191], v[0:3]
	s_setprio 0
	s_barrier
	s_add_i32 s62, 0, 0x18000
	s_add_i32 s63, 0, 0x1c000
	v_add_u32_e32 v140, s62, v228
	v_add_u32_e32 v156, s63, v228
	ds_read_b128 v[128:131], v140
	ds_read_b128 v[132:135], v140 offset:1024
	ds_read_b128 v[136:139], v140 offset:2048
	ds_read_b128 v[140:143], v140 offset:3072
	ds_read_b128 v[144:147], v156
	ds_read_b128 v[148:151], v156 offset:1024
	ds_read_b128 v[152:155], v156 offset:2048
	ds_read_b128 v[156:159], v156 offset:3072
	s_add_u32 s2, s34, 0xb0000
	s_addc_u32 s3, s35, 0
	s_mov_b32 m0, s38
	v_lshl_add_u64 v[216:217], s[2:3], 0, v[192:193]
	ds_read_b128 v[160:163], v232 offset:32768
	ds_read_b128 v[164:167], v232 offset:33792
	ds_read_b128 v[168:171], v232 offset:34816
	ds_read_b128 v[172:175], v232 offset:35840
	ds_read_b128 v[176:179], v232 offset:36864
	ds_read_b128 v[180:183], v232 offset:37888
	ds_read_b128 v[184:187], v232 offset:38912
	ds_read_b128 v[188:191], v232 offset:39936
	global_load_lds_dwordx4 v[216:217], off
	v_lshl_add_u64 v[216:217], s[2:3], 0, v[196:197]
	s_mov_b32 m0, s39
	s_nop 0
	global_load_lds_dwordx4 v[216:217], off
	s_waitcnt vmcnt(8)
	s_waitcnt lgkmcnt(0)
	s_barrier
	s_setprio 1
	s_waitcnt lgkmcnt(0)
	v_mfma_f32_16x16x32_bf16 v[124:127], v[128:131], v[160:163], v[124:127]
	v_mfma_f32_16x16x32_bf16 v[120:123], v[136:139], v[160:163], v[120:123]
	v_mfma_f32_16x16x32_bf16 v[108:111], v[128:131], v[168:171], v[108:111]
	v_mfma_f32_16x16x32_bf16 v[104:107], v[136:139], v[168:171], v[104:107]
	v_mfma_f32_16x16x32_bf16 v[92:95], v[128:131], v[176:179], v[92:95]
	v_mfma_f32_16x16x32_bf16 v[88:91], v[136:139], v[176:179], v[88:91]
	v_mfma_f32_16x16x32_bf16 v[76:79], v[128:131], v[184:187], v[76:79]
	v_mfma_f32_16x16x32_bf16 v[72:75], v[136:139], v[184:187], v[72:75]
	v_mfma_f32_16x16x32_bf16 v[124:127], v[132:135], v[164:167], v[124:127]
	v_mfma_f32_16x16x32_bf16 v[120:123], v[140:143], v[164:167], v[120:123]
	v_mfma_f32_16x16x32_bf16 v[108:111], v[132:135], v[172:175], v[108:111]
	v_mfma_f32_16x16x32_bf16 v[104:107], v[140:143], v[172:175], v[104:107]
	v_mfma_f32_16x16x32_bf16 v[92:95], v[132:135], v[180:183], v[92:95]
	v_mfma_f32_16x16x32_bf16 v[88:91], v[140:143], v[180:183], v[88:91]
	v_mfma_f32_16x16x32_bf16 v[76:79], v[132:135], v[188:191], v[76:79]
	v_mfma_f32_16x16x32_bf16 v[72:75], v[140:143], v[188:191], v[72:75]
	s_setprio 0
	s_setprio 1
	v_mfma_f32_16x16x32_bf16 v[116:119], v[144:147], v[160:163], v[116:119]
	v_mfma_f32_16x16x32_bf16 v[112:115], v[152:155], v[160:163], v[112:115]
	v_mfma_f32_16x16x32_bf16 v[100:103], v[144:147], v[168:171], v[100:103]
	v_mfma_f32_16x16x32_bf16 v[96:99], v[152:155], v[168:171], v[96:99]
	v_mfma_f32_16x16x32_bf16 v[84:87], v[144:147], v[176:179], v[84:87]
	v_mfma_f32_16x16x32_bf16 v[80:83], v[152:155], v[176:179], v[80:83]
	v_mfma_f32_16x16x32_bf16 v[68:71], v[144:147], v[184:187], v[68:71]
	v_mfma_f32_16x16x32_bf16 v[64:67], v[152:155], v[184:187], v[64:67]
	v_mfma_f32_16x16x32_bf16 v[116:119], v[148:151], v[164:167], v[116:119]
	v_mfma_f32_16x16x32_bf16 v[112:115], v[156:159], v[164:167], v[112:115]
	v_mfma_f32_16x16x32_bf16 v[100:103], v[148:151], v[172:175], v[100:103]
	v_mfma_f32_16x16x32_bf16 v[96:99], v[156:159], v[172:175], v[96:99]
	v_mfma_f32_16x16x32_bf16 v[84:87], v[148:151], v[180:183], v[84:87]
	v_mfma_f32_16x16x32_bf16 v[80:83], v[156:159], v[180:183], v[80:83]
	v_mfma_f32_16x16x32_bf16 v[68:71], v[148:151], v[188:191], v[68:71]
	v_mfma_f32_16x16x32_bf16 v[64:67], v[156:159], v[188:191], v[64:67]
	s_setprio 0
	s_barrier
	s_add_i32 s2, s62, s33
	v_lshl_add_u64 v[208:209], v[208:209], 0, s[12:13]
	s_mov_b32 m0, s2
	ds_read_b128 v[160:163], v232 offset:49152
	ds_read_b128 v[164:167], v232 offset:50176
	ds_read_b128 v[168:171], v232 offset:51200
	ds_read_b128 v[172:175], v232 offset:52224
	ds_read_b128 v[176:179], v232 offset:53248
	ds_read_b128 v[180:183], v232 offset:54272
	ds_read_b128 v[184:187], v232 offset:55296
	ds_read_b128 v[188:191], v232 offset:56320
	global_load_lds_dwordx4 v[208:209], off
	s_add_i32 m0, s2, 0x2000
	s_add_u32 s2, s26, 0xb0080
	v_lshl_add_u64 v[208:209], v[210:211], 0, s[12:13]
	s_addc_u32 s3, s27, 0
	s_add_i32 s26, s63, s33
	global_load_lds_dwordx4 v[208:209], off
	v_lshl_add_u64 v[208:209], s[2:3], 0, v[194:195]
	s_mov_b32 m0, s26
	s_nop 0
	global_load_lds_dwordx4 v[208:209], off
	v_lshl_add_u64 v[208:209], s[2:3], 0, v[198:199]
	s_add_i32 m0, s26, 0x2000
	s_nop 0
	global_load_lds_dwordx4 v[208:209], off
	v_lshl_add_u64 v[208:209], v[212:213], 0, s[12:13]
	s_mov_b32 m0, s46
	s_nop 0
	global_load_lds_dwordx4 v[208:209], off
	v_lshl_add_u64 v[208:209], v[214:215], 0, s[12:13]
	s_mov_b32 m0, s47
	s_nop 0
	global_load_lds_dwordx4 v[208:209], off
	s_waitcnt vmcnt(8)
	s_waitcnt lgkmcnt(0)
	s_barrier
	s_setprio 1
	s_waitcnt lgkmcnt(0)
	v_mfma_f32_16x16x32_bf16 v[60:63], v[128:131], v[160:163], v[60:63]
	v_mfma_f32_16x16x32_bf16 v[56:59], v[136:139], v[160:163], v[56:59]
	v_mfma_f32_16x16x32_bf16 v[44:47], v[128:131], v[168:171], v[44:47]
	v_mfma_f32_16x16x32_bf16 v[40:43], v[136:139], v[168:171], v[40:43]
	v_mfma_f32_16x16x32_bf16 v[28:31], v[128:131], v[176:179], v[28:31]
	v_mfma_f32_16x16x32_bf16 v[24:27], v[136:139], v[176:179], v[24:27]
	v_mfma_f32_16x16x32_bf16 v[12:15], v[128:131], v[184:187], v[12:15]
	v_mfma_f32_16x16x32_bf16 v[8:11], v[136:139], v[184:187], v[8:11]
	v_mfma_f32_16x16x32_bf16 v[60:63], v[132:135], v[164:167], v[60:63]
	v_mfma_f32_16x16x32_bf16 v[56:59], v[140:143], v[164:167], v[56:59]
	v_mfma_f32_16x16x32_bf16 v[44:47], v[132:135], v[172:175], v[44:47]
	v_mfma_f32_16x16x32_bf16 v[40:43], v[140:143], v[172:175], v[40:43]
	v_mfma_f32_16x16x32_bf16 v[28:31], v[132:135], v[180:183], v[28:31]
	v_mfma_f32_16x16x32_bf16 v[24:27], v[140:143], v[180:183], v[24:27]
	v_mfma_f32_16x16x32_bf16 v[12:15], v[132:135], v[188:191], v[12:15]
	v_mfma_f32_16x16x32_bf16 v[8:11], v[140:143], v[188:191], v[8:11]
	s_setprio 0
	s_setprio 1
	v_mfma_f32_16x16x32_bf16 v[52:55], v[144:147], v[160:163], v[52:55]
	v_mfma_f32_16x16x32_bf16 v[48:51], v[152:155], v[160:163], v[48:51]
	v_mfma_f32_16x16x32_bf16 v[36:39], v[144:147], v[168:171], v[36:39]
	v_mfma_f32_16x16x32_bf16 v[32:35], v[152:155], v[168:171], v[32:35]
	v_mfma_f32_16x16x32_bf16 v[20:23], v[144:147], v[176:179], v[20:23]
	v_mfma_f32_16x16x32_bf16 v[16:19], v[152:155], v[176:179], v[16:19]
	v_mfma_f32_16x16x32_bf16 v[4:7], v[144:147], v[184:187], v[4:7]
	v_mfma_f32_16x16x32_bf16 v[0:3], v[152:155], v[184:187], v[0:3]
	v_mfma_f32_16x16x32_bf16 v[52:55], v[148:151], v[164:167], v[52:55]
	v_mfma_f32_16x16x32_bf16 v[48:51], v[156:159], v[164:167], v[48:51]
	v_mfma_f32_16x16x32_bf16 v[36:39], v[148:151], v[172:175], v[36:39]
	v_mfma_f32_16x16x32_bf16 v[32:35], v[156:159], v[172:175], v[32:35]
	v_mfma_f32_16x16x32_bf16 v[20:23], v[148:151], v[180:183], v[20:23]
	v_mfma_f32_16x16x32_bf16 v[16:19], v[156:159], v[180:183], v[16:19]
	v_mfma_f32_16x16x32_bf16 v[4:7], v[148:151], v[188:191], v[4:7]
	v_mfma_f32_16x16x32_bf16 v[0:3], v[156:159], v[188:191], v[0:3]
	s_setprio 0
	s_add_i32 s61, s61, 2
	s_add_u32 s59, s59, 0x100
	s_addc_u32 s60, s60, 0
	s_cmp_gt_u32 s61, s101
	s_mov_b64 s[2:3], s[24:25]
	s_barrier
	s_cbranch_scc0 .LBB0_1044
	s_and_b64 vcc, exec, s[14:15]
	s_cbranch_vccz .LBB0_1047
	s_barrier
